# in-proj column tile 14: in its K-loop copy the waves of column groups 1..3 skip fragment reads and MFMAs (results never stored), unused fragment reads dropped
# speedup vs baseline: 1.0001x; 1.0001x over previous
.Lz255:
	s_add_u32 s88, s8, 0x100
	s_addc_u32 s89, s9, 0
	s_add_u32 s8, s38, 0x40080
	s_addc_u32 s9, s39, 0
	s_mov_b32 s90, -2
	s_add_u32 s38, s8, 0xfffc0080
	s_addc_u32 s39, s9, -1
	s_add_i32 s91, 0, 0x10000
	s_cmp_eq_u32 s90, 12
	s_cselect_b32 s57, s31, s39
	s_cselect_b32 s56, s47, s38
	s_cselect_b32 s39, s29, s89
	s_cselect_b32 s38, s87, s88
	s_add_i32 s94, 0, 0x14000
	v_add_u32_e32 v140, s91, v183
	v_add_u32_e32 v168, s94, v183
	s_and_b32 s98, s33, 0xc0
	s_cbranch_scc1 .Lzs1
	ds_read_b128 v[128:131], v140
	ds_read_b128 v[132:135], v140 offset:1024
	ds_read_b128 v[136:139], v140 offset:2048
	ds_read_b128 v[140:143], v140 offset:3072
.Lzs1:
	v_lshl_add_u64 v[184:185], s[8:9], 0, v[162:163]
	s_add_i32 m0, s55, 0xc000
	s_and_b32 s98, s33, 0xc0
	s_cbranch_scc1 .Lzs2
	ds_read_b128 v[172:175], v187
	ds_read_b128 v[176:179], v187 offset:1024
	ds_read_b128 v[188:191], v187 offset:2048
	ds_read_b128 v[202:205], v187 offset:3072
	ds_read_b128 v[206:209], v187 offset:4096
	ds_read_b128 v[210:213], v187 offset:5120
	ds_read_b128 v[214:217], v187 offset:6144
	ds_read_b128 v[218:221], v187 offset:7168
.Lzs2:
	global_load_lds_dwordx4 v[184:185], off
	v_lshl_add_u64 v[184:185], s[8:9], 0, v[160:161]
	s_add_i32 m0, s55, 0xe000
	s_nop 0
	global_load_lds_dwordx4 v[184:185], off
	s_add_i32 s85, s85, 1
	s_mul_i32 s6, s85, s43
	s_mul_hi_u32 s7, s85, s42
	s_add_i32 s7, s7, s6
	s_mul_i32 s6, s85, s42
	s_add_u32 s34, s6, s2
	s_addc_u32 s35, s7, s41
	v_mov_b64_e32 v[0:1], 0xf00
	v_cmp_lt_i64_e64 s[6:7], s[34:35], v[0:1]
	v_mov_b64_e32 v[0:1], 0xeff
	v_cmp_gt_i64_e32 vcc, s[34:35], v[0:1]
	s_cbranch_vccnz .Lz257
	s_ashr_i32 s28, s34, 31
	s_lshr_b32 s28, s28, 29
	s_add_i32 s28, s34, s28
	s_ashr_i32 s29, s28, 3
	s_and_b32 s28, s28, -8
	s_sub_i32 s28, s34, s28
	s_cmp_lt_i32 s28, 0
	s_movk_i32 s30, 0x1e1
	s_cselect_b32 s30, s30, 0x1e0
	s_mul_i32 s28, s28, s30
	s_add_i32 s28, s28, s29
	s_mul_hi_i32 s29, s28, 0x88888889
	s_add_i32 s29, s29, s28
	s_lshr_b32 s30, s29, 31
	s_ashr_i32 s29, s29, 6
	s_add_i32 s29, s29, s30
	s_lshl_b32 s30, s29, 3
	s_sub_i32 s31, 0x100, s30
	s_min_i32 s31, s31, 8
	s_abs_i32 s34, s31
	v_cvt_f32_u32_e32 v0, s34
	s_sub_i32 s36, 0, s34
	s_mulk_i32 s29, 0x78
	s_sub_i32 s29, s28, s29
	v_rcp_iflag_f32_e32 v0, v0
	s_abs_i32 s28, s29
	s_xor_b32 s35, s29, s31
	s_ashr_i32 s35, s35, 31
	v_mul_f32_e32 v0, 0x4f7ffffe, v0
	v_cvt_u32_f32_e32 v0, v0
	s_nop 0
	v_readfirstlane_b32 s37, v0
	s_mul_i32 s36, s36, s37
	s_mul_hi_u32 s36, s37, s36
	s_add_i32 s37, s37, s36
	s_mul_hi_u32 s36, s28, s37
	s_mul_i32 s37, s36, s34
	s_sub_i32 s28, s28, s37
	s_add_i32 s47, s36, 1
	s_sub_i32 s37, s28, s34
	s_cmp_ge_u32 s28, s34
	s_cselect_b32 s36, s47, s36
	s_cselect_b32 s28, s37, s28
	s_add_i32 s37, s36, 1
	s_cmp_ge_u32 s28, s34
	s_cselect_b32 s28, s37, s36
	s_xor_b32 s28, s28, s35
	s_sub_i32 s28, s28, s35
	s_mul_i32 s31, s28, s31
	s_sub_i32 s29, s29, s31
	s_add_i32 s30, s30, s29
.Lz257:
	s_ashr_i32 s31, s30, 31
	s_lshl_b64 s[34:35], s[30:31], 19
	s_add_u32 s34, s48, s34
	s_addc_u32 s35, s49, s35
	s_and_b64 s[36:37], s[6:7], exec
	s_cselect_b32 s31, s35, s57
	s_cselect_b32 s47, s34, s56
	s_ashr_i32 s29, s28, 31
	s_lshl_b64 s[36:37], s[28:29], 19
	s_add_u32 s36, s50, s36
	s_addc_u32 s37, s51, s37
	s_and_b64 s[100:101], s[6:7], exec
	s_cselect_b32 s29, s37, s89
	s_cselect_b32 s87, s36, s88
	s_waitcnt vmcnt(8)
	s_waitcnt lgkmcnt(0)
	s_barrier
	s_setprio 1
	s_waitcnt lgkmcnt(0)
	s_and_b32 s98, s33, 0xc0
	s_cbranch_scc1 .Lzs3
	v_mfma_f32_16x16x32_bf16 v[124:127], v[128:131], v[172:175], 0
	v_mfma_f32_16x16x32_bf16 v[120:123], v[136:139], v[172:175], 0
	v_mfma_f32_16x16x32_bf16 v[112:115], v[128:131], v[188:191], 0
	v_mfma_f32_16x16x32_bf16 v[104:107], v[136:139], v[188:191], 0
	v_mfma_f32_16x16x32_bf16 v[96:99], v[128:131], v[206:209], 0
	v_mfma_f32_16x16x32_bf16 v[88:91], v[136:139], v[206:209], 0
	v_mfma_f32_16x16x32_bf16 v[80:83], v[128:131], v[214:217], 0
	v_mfma_f32_16x16x32_bf16 v[72:75], v[136:139], v[214:217], 0
	v_mfma_f32_16x16x32_bf16 v[124:127], v[132:135], v[176:179], v[124:127]
	v_mfma_f32_16x16x32_bf16 v[120:123], v[140:143], v[176:179], v[120:123]
	v_mfma_f32_16x16x32_bf16 v[112:115], v[132:135], v[202:205], v[112:115]
	v_mfma_f32_16x16x32_bf16 v[104:107], v[140:143], v[202:205], v[104:107]
	v_mfma_f32_16x16x32_bf16 v[96:99], v[132:135], v[210:213], v[96:99]
	v_mfma_f32_16x16x32_bf16 v[88:91], v[140:143], v[210:213], v[88:91]
	v_mfma_f32_16x16x32_bf16 v[80:83], v[132:135], v[218:221], v[80:83]
	v_mfma_f32_16x16x32_bf16 v[72:75], v[140:143], v[218:221], v[72:75]
.Lzs3:
	s_setprio 0
	s_setprio 1
	s_setprio 0
	s_barrier
	s_add_i32 s91, s91, s54
	v_lshl_add_u64 v[184:185], s[38:39], 0, v[192:193]
	s_mov_b32 m0, s91
	s_and_b32 s98, s33, 0xc0
	s_cbranch_scc1 .Lzs4
	ds_read_b128 v[172:175], v187 offset:16384
	ds_read_b128 v[176:179], v187 offset:17408
	ds_read_b128 v[188:191], v187 offset:18432
	ds_read_b128 v[202:205], v187 offset:19456
	ds_read_b128 v[206:209], v187 offset:20480
	ds_read_b128 v[210:213], v187 offset:21504
	ds_read_b128 v[214:217], v187 offset:22528
	ds_read_b128 v[218:221], v187 offset:23552
.Lzs4:
	global_load_lds_dwordx4 v[184:185], off
	s_add_i32 m0, s91, 0x2000
	s_add_u32 s92, s38, 0x40000
	v_lshl_add_u64 v[222:223], s[38:39], 0, v[152:153]
	s_addc_u32 s93, s39, 0
	s_add_i32 s91, s94, s54
	global_load_lds_dwordx4 v[222:223], off
	v_lshl_add_u64 v[224:225], s[92:93], 0, v[192:193]
	s_mov_b32 m0, s91
	v_lshl_add_u64 v[226:227], s[56:57], 0, v[154:155]
	global_load_lds_dwordx4 v[224:225], off
	v_lshl_add_u64 v[224:225], s[92:93], 0, v[152:153]
	s_add_i32 m0, s91, 0x2000
	s_nop 0
	global_load_lds_dwordx4 v[224:225], off
	v_lshl_add_u64 v[224:225], s[56:57], 0, v[156:157]
	s_mov_b32 m0, s55
	s_nop 0
	global_load_lds_dwordx4 v[224:225], off
	s_mov_b32 m0, s60
	s_nop 0
	global_load_lds_dwordx4 v[226:227], off
	s_waitcnt vmcnt(8)
	s_waitcnt lgkmcnt(0)
	s_barrier
	s_setprio 1
	s_waitcnt lgkmcnt(0)
	s_and_b32 s98, s33, 0xc0
	s_cbranch_scc1 .Lzs5
	v_mfma_f32_16x16x32_bf16 v[60:63], v[128:131], v[172:175], 0
	v_mfma_f32_16x16x32_bf16 v[56:59], v[136:139], v[172:175], 0
	v_mfma_f32_16x16x32_bf16 v[48:51], v[128:131], v[188:191], 0
	v_mfma_f32_16x16x32_bf16 v[40:43], v[136:139], v[188:191], 0
	v_mfma_f32_16x16x32_bf16 v[32:35], v[128:131], v[206:209], 0
	v_mfma_f32_16x16x32_bf16 v[24:27], v[136:139], v[206:209], 0
	v_mfma_f32_16x16x32_bf16 v[16:19], v[128:131], v[214:217], 0
	v_mfma_f32_16x16x32_bf16 v[8:11], v[136:139], v[214:217], 0
	v_mfma_f32_16x16x32_bf16 v[60:63], v[132:135], v[176:179], v[60:63]
	v_mfma_f32_16x16x32_bf16 v[56:59], v[140:143], v[176:179], v[56:59]
	v_mfma_f32_16x16x32_bf16 v[48:51], v[132:135], v[202:205], v[48:51]
	v_mfma_f32_16x16x32_bf16 v[40:43], v[140:143], v[202:205], v[40:43]
	v_mfma_f32_16x16x32_bf16 v[32:35], v[132:135], v[210:213], v[32:35]
	v_mfma_f32_16x16x32_bf16 v[24:27], v[140:143], v[210:213], v[24:27]
	v_mfma_f32_16x16x32_bf16 v[16:19], v[132:135], v[218:221], v[16:19]
	v_mfma_f32_16x16x32_bf16 v[8:11], v[140:143], v[218:221], v[8:11]
.Lzs5:
	s_setprio 0
	s_setprio 1
	s_setprio 0
	s_barrier
	s_add_i32 s91, 0, 0x18000
	s_add_i32 s92, 0, 0x1c000
	v_add_u32_e32 v140, s91, v183
	v_add_u32_e32 v168, s92, v183
	s_and_b32 s98, s33, 0xc0
	s_cbranch_scc1 .Lzs6
	ds_read_b128 v[128:131], v140
	ds_read_b128 v[132:135], v140 offset:1024
	ds_read_b128 v[136:139], v140 offset:2048
	ds_read_b128 v[140:143], v140 offset:3072
.Lzs6:
	s_add_u32 s56, s56, 0x40000
	s_addc_u32 s57, s57, 0
	s_mov_b32 m0, s61
	v_lshl_add_u64 v[228:229], s[56:57], 0, v[156:157]
	s_and_b32 s98, s33, 0xc0
	s_cbranch_scc1 .Lzs7
	ds_read_b128 v[172:175], v187 offset:32768
	ds_read_b128 v[176:179], v187 offset:33792
	ds_read_b128 v[188:191], v187 offset:34816
	ds_read_b128 v[202:205], v187 offset:35840
	ds_read_b128 v[206:209], v187 offset:36864
	ds_read_b128 v[210:213], v187 offset:37888
	ds_read_b128 v[214:217], v187 offset:38912
	ds_read_b128 v[218:221], v187 offset:39936
.Lzs7:
	global_load_lds_dwordx4 v[228:229], off
	v_lshl_add_u64 v[228:229], s[56:57], 0, v[154:155]
	s_mov_b32 m0, s82
	s_nop 0
	global_load_lds_dwordx4 v[228:229], off
	s_waitcnt vmcnt(8)
	s_waitcnt lgkmcnt(0)
	s_barrier
	s_setprio 1
	s_waitcnt lgkmcnt(0)
	s_and_b32 s98, s33, 0xc0
	s_cbranch_scc1 .Lzs8
	v_mfma_f32_16x16x32_bf16 v[124:127], v[128:131], v[172:175], v[124:127]
	v_mfma_f32_16x16x32_bf16 v[120:123], v[136:139], v[172:175], v[120:123]
	v_mfma_f32_16x16x32_bf16 v[112:115], v[128:131], v[188:191], v[112:115]
	v_mfma_f32_16x16x32_bf16 v[104:107], v[136:139], v[188:191], v[104:107]
	v_mfma_f32_16x16x32_bf16 v[96:99], v[128:131], v[206:209], v[96:99]
	v_mfma_f32_16x16x32_bf16 v[88:91], v[136:139], v[206:209], v[88:91]
	v_mfma_f32_16x16x32_bf16 v[80:83], v[128:131], v[214:217], v[80:83]
	v_mfma_f32_16x16x32_bf16 v[72:75], v[136:139], v[214:217], v[72:75]
	v_mfma_f32_16x16x32_bf16 v[124:127], v[132:135], v[176:179], v[124:127]
	v_mfma_f32_16x16x32_bf16 v[120:123], v[140:143], v[176:179], v[120:123]
	v_mfma_f32_16x16x32_bf16 v[112:115], v[132:135], v[202:205], v[112:115]
	v_mfma_f32_16x16x32_bf16 v[104:107], v[140:143], v[202:205], v[104:107]
	v_mfma_f32_16x16x32_bf16 v[96:99], v[132:135], v[210:213], v[96:99]
	v_mfma_f32_16x16x32_bf16 v[88:91], v[140:143], v[210:213], v[88:91]
	v_mfma_f32_16x16x32_bf16 v[80:83], v[132:135], v[218:221], v[80:83]
	v_mfma_f32_16x16x32_bf16 v[72:75], v[140:143], v[218:221], v[72:75]
.Lzs8:
	s_setprio 0
	s_setprio 1
	s_setprio 0
	s_barrier
	s_add_i32 s56, s91, s54
	v_lshl_add_u64 v[184:185], v[184:185], 0, s[76:77]
	s_mov_b32 m0, s56
	s_and_b32 s98, s33, 0xc0
	s_cbranch_scc1 .Lzs9
	ds_read_b128 v[172:175], v187 offset:49152
	ds_read_b128 v[176:179], v187 offset:50176
	ds_read_b128 v[188:191], v187 offset:51200
	ds_read_b128 v[202:205], v187 offset:52224
	ds_read_b128 v[206:209], v187 offset:53248
	ds_read_b128 v[210:213], v187 offset:54272
	ds_read_b128 v[214:217], v187 offset:55296
	ds_read_b128 v[218:221], v187 offset:56320
.Lzs9:
	global_load_lds_dwordx4 v[184:185], off
	s_add_i32 m0, s56, 0x2000
	s_add_u32 s38, s38, 0x40080
	v_lshl_add_u64 v[184:185], v[222:223], 0, s[76:77]
	s_addc_u32 s39, s39, 0
	s_add_i32 s56, s92, s54
	global_load_lds_dwordx4 v[184:185], off
	v_lshl_add_u64 v[184:185], s[38:39], 0, v[192:193]
	s_mov_b32 m0, s56
	s_nop 0
	global_load_lds_dwordx4 v[184:185], off
	v_lshl_add_u64 v[184:185], s[38:39], 0, v[152:153]
	s_add_i32 m0, s56, 0x2000
	s_nop 0
	global_load_lds_dwordx4 v[184:185], off
	v_lshl_add_u64 v[184:185], v[224:225], 0, s[76:77]
	s_mov_b32 m0, s68
	s_nop 0
	global_load_lds_dwordx4 v[184:185], off
	v_lshl_add_u64 v[184:185], v[226:227], 0, s[76:77]
	s_mov_b32 m0, s83
	s_nop 0
	global_load_lds_dwordx4 v[184:185], off
	s_waitcnt vmcnt(8)
	s_waitcnt lgkmcnt(0)
	s_barrier
	s_setprio 1
	s_waitcnt lgkmcnt(0)
	s_and_b32 s98, s33, 0xc0
	s_cbranch_scc1 .Lzs10
	v_mfma_f32_16x16x32_bf16 v[60:63], v[128:131], v[172:175], v[60:63]
	v_mfma_f32_16x16x32_bf16 v[56:59], v[136:139], v[172:175], v[56:59]
	v_mfma_f32_16x16x32_bf16 v[48:51], v[128:131], v[188:191], v[48:51]
	v_mfma_f32_16x16x32_bf16 v[40:43], v[136:139], v[188:191], v[40:43]
	v_mfma_f32_16x16x32_bf16 v[32:35], v[128:131], v[206:209], v[32:35]
	v_mfma_f32_16x16x32_bf16 v[24:27], v[136:139], v[206:209], v[24:27]
	v_mfma_f32_16x16x32_bf16 v[16:19], v[128:131], v[214:217], v[16:19]
	v_mfma_f32_16x16x32_bf16 v[8:11], v[136:139], v[214:217], v[8:11]
	v_mfma_f32_16x16x32_bf16 v[60:63], v[132:135], v[176:179], v[60:63]
	v_mfma_f32_16x16x32_bf16 v[56:59], v[140:143], v[176:179], v[56:59]
	v_mfma_f32_16x16x32_bf16 v[48:51], v[132:135], v[202:205], v[48:51]
	v_mfma_f32_16x16x32_bf16 v[40:43], v[140:143], v[202:205], v[40:43]
	v_mfma_f32_16x16x32_bf16 v[32:35], v[132:135], v[210:213], v[32:35]
	v_mfma_f32_16x16x32_bf16 v[24:27], v[140:143], v[210:213], v[24:27]
	v_mfma_f32_16x16x32_bf16 v[16:19], v[132:135], v[218:221], v[16:19]
	v_mfma_f32_16x16x32_bf16 v[8:11], v[140:143], v[218:221], v[8:11]
.Lzs10:
	s_setprio 0
	s_setprio 1
	s_setprio 0
	s_barrier
	s_add_i32 s90, s90, 2
	s_add_u32 s88, s88, 0x100
	s_addc_u32 s89, s89, 0
	s_add_u32 s8, s8, 0x100
	s_addc_u32 s9, s9, 0
	s_cmp_gt_u32 s90, 13
.Lz258:
	s_add_u32 s38, s8, 0xfffc0080
	s_addc_u32 s39, s9, -1
	s_add_i32 s91, 0, 0x10000
	s_cmp_eq_u32 s90, 12
	s_cselect_b32 s57, s31, s39
	s_cselect_b32 s56, s47, s38
	s_cselect_b32 s39, s29, s89
	s_cselect_b32 s38, s87, s88
	s_add_i32 s94, 0, 0x14000
	v_add_u32_e32 v140, s91, v183
	v_add_u32_e32 v168, s94, v183
	s_and_b32 s98, s33, 0xc0
	s_cbranch_scc1 .Lzs11
	ds_read_b128 v[128:131], v140
	ds_read_b128 v[132:135], v140 offset:1024
	ds_read_b128 v[136:139], v140 offset:2048
	ds_read_b128 v[140:143], v140 offset:3072

.Lzs12:
	global_load_lds_dwordx4 v[184:185], off
	v_lshl_add_u64 v[184:185], s[8:9], 0, v[160:161]
	s_add_i32 m0, s55, 0xe000
	s_nop 0
	global_load_lds_dwordx4 v[184:185], off
	s_waitcnt vmcnt(8)
	s_waitcnt lgkmcnt(0)
	s_barrier
	s_setprio 1
	s_waitcnt lgkmcnt(0)
	s_and_b32 s98, s33, 0xc0
	s_cbranch_scc1 .Lzs13
	v_mfma_f32_16x16x32_bf16 v[124:127], v[128:131], v[172:175], v[124:127]
	v_mfma_f32_16x16x32_bf16 v[120:123], v[136:139], v[172:175], v[120:123]
	v_mfma_f32_16x16x32_bf16 v[112:115], v[128:131], v[188:191], v[112:115]
	v_mfma_f32_16x16x32_bf16 v[104:107], v[136:139], v[188:191], v[104:107]
	v_mfma_f32_16x16x32_bf16 v[96:99], v[128:131], v[206:209], v[96:99]
	v_mfma_f32_16x16x32_bf16 v[88:91], v[136:139], v[206:209], v[88:91]
	v_mfma_f32_16x16x32_bf16 v[80:83], v[128:131], v[214:217], v[80:83]
	v_mfma_f32_16x16x32_bf16 v[72:75], v[136:139], v[214:217], v[72:75]
	v_mfma_f32_16x16x32_bf16 v[124:127], v[132:135], v[176:179], v[124:127]
	v_mfma_f32_16x16x32_bf16 v[120:123], v[140:143], v[176:179], v[120:123]
	v_mfma_f32_16x16x32_bf16 v[112:115], v[132:135], v[202:205], v[112:115]
	v_mfma_f32_16x16x32_bf16 v[104:107], v[140:143], v[202:205], v[104:107]
	v_mfma_f32_16x16x32_bf16 v[96:99], v[132:135], v[210:213], v[96:99]
	v_mfma_f32_16x16x32_bf16 v[88:91], v[140:143], v[210:213], v[88:91]
	v_mfma_f32_16x16x32_bf16 v[80:83], v[132:135], v[218:221], v[80:83]
	v_mfma_f32_16x16x32_bf16 v[72:75], v[140:143], v[218:221], v[72:75]

.Lzs14:
	global_load_lds_dwordx4 v[184:185], off
	s_add_i32 m0, s91, 0x2000
	s_add_u32 s92, s38, 0x40000
	v_lshl_add_u64 v[222:223], s[38:39], 0, v[152:153]
	s_addc_u32 s93, s39, 0
	s_add_i32 s91, s94, s54
	global_load_lds_dwordx4 v[222:223], off
	v_lshl_add_u64 v[224:225], s[92:93], 0, v[192:193]
	s_mov_b32 m0, s91
	v_lshl_add_u64 v[226:227], s[56:57], 0, v[154:155]
	global_load_lds_dwordx4 v[224:225], off
	v_lshl_add_u64 v[224:225], s[92:93], 0, v[152:153]
	s_add_i32 m0, s91, 0x2000
	s_nop 0
	global_load_lds_dwordx4 v[224:225], off
	v_lshl_add_u64 v[224:225], s[56:57], 0, v[156:157]
	s_mov_b32 m0, s55
	s_nop 0
	global_load_lds_dwordx4 v[224:225], off
	s_mov_b32 m0, s60
	s_nop 0
	global_load_lds_dwordx4 v[226:227], off
	s_waitcnt vmcnt(8)
	s_waitcnt lgkmcnt(0)
	s_barrier
	s_setprio 1
	s_waitcnt lgkmcnt(0)
	s_and_b32 s98, s33, 0xc0
	s_cbranch_scc1 .Lzs15
	v_mfma_f32_16x16x32_bf16 v[60:63], v[128:131], v[172:175], v[60:63]
	v_mfma_f32_16x16x32_bf16 v[56:59], v[136:139], v[172:175], v[56:59]
	v_mfma_f32_16x16x32_bf16 v[48:51], v[128:131], v[188:191], v[48:51]
	v_mfma_f32_16x16x32_bf16 v[40:43], v[136:139], v[188:191], v[40:43]
	v_mfma_f32_16x16x32_bf16 v[32:35], v[128:131], v[206:209], v[32:35]
	v_mfma_f32_16x16x32_bf16 v[24:27], v[136:139], v[206:209], v[24:27]
	v_mfma_f32_16x16x32_bf16 v[16:19], v[128:131], v[214:217], v[16:19]
	v_mfma_f32_16x16x32_bf16 v[8:11], v[136:139], v[214:217], v[8:11]
	v_mfma_f32_16x16x32_bf16 v[60:63], v[132:135], v[176:179], v[60:63]
	v_mfma_f32_16x16x32_bf16 v[56:59], v[140:143], v[176:179], v[56:59]
	v_mfma_f32_16x16x32_bf16 v[48:51], v[132:135], v[202:205], v[48:51]
	v_mfma_f32_16x16x32_bf16 v[40:43], v[140:143], v[202:205], v[40:43]
	v_mfma_f32_16x16x32_bf16 v[32:35], v[132:135], v[210:213], v[32:35]
	v_mfma_f32_16x16x32_bf16 v[24:27], v[140:143], v[210:213], v[24:27]
	v_mfma_f32_16x16x32_bf16 v[16:19], v[132:135], v[218:221], v[16:19]
	v_mfma_f32_16x16x32_bf16 v[8:11], v[140:143], v[218:221], v[8:11]

.Lzs20:
	s_setprio 0
	s_setprio 1
	s_setprio 0
	s_barrier
	s_add_i32 s90, s90, 2
	s_add_u32 s88, s88, 0x100
	s_addc_u32 s89, s89, 0
	s_add_u32 s8, s8, 0x100
	s_addc_u32 s9, s9, 0
	s_cmp_gt_u32 s90, 13
	s_cbranch_scc0 .Lz258
	s_branch .LBB0_261
